# attention PV: first V-fragment read pair of each step issued right after the previous MFMA so its LDS latency hides behind the exp/cvt block
# speedup vs baseline: 1.0084x; 1.0001x over previous
; #define LAS __attribute__((address_space(3)))
; __device__ __forceinline__ int crow(int r, int hi) { return (r & 3) + 8 * (r >> 2) + 4 * hi; }
; __device__ __forceinline__ void attn_phase(LAS unsigned char* lds, const bf16_t* qp, const bf16_t* kvp, bf16_t* obuf, float* lse, const float* biasG, const int gi, const int rsh, const int G) {
;     ...
;         const int c0 = ((2 * j) % 3) * 4 + w;
;         int sc[5];
; #pragma unroll
;         for (int cc = 0; cc < 5; ++cc) { const int t = c0 + cc; sc[cc] = t >= 12 ? t - 12 : t; }
;         f32x16 p[5];
;         const LAS float* bt = (const LAS float*)(lds + A_BT);
;         const LAS unsigned char* kbase = lds + A_K0 + hi * KCS + r32 * 16;
; #pragma unroll
;         for (int c2 = 0; c2 < 5; c2 += 2) {
;             bf16x8 ka[4], kb[4];
; #pragma unroll
;             for (int d0 = 0; d0 < 4; ++d0) { ka[d0] = *(const LAS bf16x8*)(kbase + 2 * d0 * KCS + sc[c2] * 512); if (c2 + 1 < 5) kb[d0] = *(const LAS bf16x8*)(kbase + 2 * d0 * KCS + sc[c2 + 1 < 5 ? c2 + 1 : c2] * 512); }
; #pragma unroll
;             for (int q = 0; q < 2; ++q) { const int cc = c2 + q; if (cc < 5) { const bool dead = (np == 0) && (w + cc < 4);
;                 const LAS float* bq_ = dead ? bt + 27 - (160 + r32 - 32 * cc - 4 * hi) : bt;
; #pragma unroll
;                 for (int r = 0; r < 16; ++r) p[cc][r] = bq_[160 + r32 - 32 * cc - crow(r, hi)]; } }
;             __builtin_amdgcn_sched_barrier(0);
; #pragma unroll
;             for (int d0 = 0; d0 < 4; ++d0) {
;                 p[c2] = __builtin_amdgcn_mfma_f32_32x32x16_bf16(ka[d0], qr[d0], p[c2], 0, 0, 0);
;                 if (c2 + 1 < 5) p[c2 + 1 < 5 ? c2 + 1 : c2] = __builtin_amdgcn_mfma_f32_32x32x16_bf16(kb[d0], qr[d0], p[c2 + 1 < 5 ? c2 + 1 : c2], 0, 0, 0);
;             }
;             __builtin_amdgcn_sched_barrier(0);
;         }
.LBB0_115:
	s_lshl_b32 s2, s22, 1
	s_mulk_i32 s22, 0xac
	s_lshr_b32 s3, s22, 8
	s_mul_i32 s3, s3, 3
	s_sub_i32 s2, s2, s3
	s_lshl_b32 s2, s2, 2
	s_and_b32 s2, s2, 0xfc
	s_add_i32 s2, s10, s2
	s_add_i32 s3, s2, -12
	s_cmp_gt_i32 s2, 11
	s_cselect_b32 s27, s3, s2
	s_cmp_gt_i32 s2, 10
	s_cselect_b32 s26, -11, 1
	s_add_i32 s26, s26, s2
	s_cmp_gt_i32 s2, 9
	s_cselect_b32 s23, -10, 2
	s_add_i32 s23, s23, s2
	s_cmp_gt_i32 s2, 8
	s_cselect_b32 s22, -9, 3
	s_add_i32 s22, s22, s2
	s_cmp_gt_i32 s2, 7
	s_cselect_b32 s4, -8, 4
	s_add_i32 s4, s4, s2
	v_readlane_b32 s2, v254, 37
	v_lshl_add_u32 v0, s27, 9, v243
	s_and_b64 vcc, s[46:47], s[52:53]
	v_mov_b32_e32 v186, s2
	v_lshl_add_u32 v1, s26, 9, v243
	ds_read_b128 v[32:35], v0 offset:12320
	ds_read_b128 v[36:39], v0 offset:24640
	ds_read_b128 v[40:43], v1 offset:12320
	ds_read_b128 v[44:47], v1 offset:24640
	ds_read_b128 v[48:51], v0
	ds_read_b128 v[52:55], v0 offset:36960
	ds_read_b128 v[56:59], v1
	ds_read_b128 v[60:63], v1 offset:36960
	v_cndmask_b32_e32 v64, v186, v245, vcc
	v_lshlrev_b32_e32 v187, 2, v238
	v_add3_u32 v64, v64, v187, v250
	ds_read2_b32 v[0:1], v64 offset0:160 offset1:159
	ds_read2_b32 v[2:3], v64 offset0:158 offset1:157
	ds_read2_b32 v[4:5], v64 offset0:152 offset1:151
	ds_read2_b32 v[6:7], v64 offset0:150 offset1:149
	ds_read2_b32 v[8:9], v64 offset0:144 offset1:143
	ds_read2_b32 v[10:11], v64 offset0:142 offset1:141
	ds_read2_b32 v[12:13], v64 offset0:136 offset1:135
	ds_read2_b32 v[14:15], v64 offset0:134 offset1:133
	s_and_b64 vcc, s[46:47], s[50:51]
	v_cndmask_b32_e32 v65, v186, v246, vcc
	v_add3_u32 v65, v65, v187, v250
	s_waitcnt lgkmcnt(8)
	ds_read2_b32 v[80:81], v65 offset0:128 offset1:127
	ds_read2_b32 v[82:83], v65 offset0:126 offset1:125
	ds_read2_b32 v[84:85], v65 offset0:120 offset1:119
	ds_read2_b32 v[86:87], v65 offset0:118 offset1:117
	ds_read2_b32 v[88:89], v65 offset0:112 offset1:111
	ds_read2_b32 v[90:91], v65 offset0:110 offset1:109
	ds_read2_b32 v[92:93], v65 offset0:104 offset1:103
	ds_read2_b32 v[94:95], v65 offset0:102 offset1:101
	s_waitcnt lgkmcnt(0)
	v_mfma_f32_32x32x16_bf16 v[0:15], v[48:51], v[28:31], v[0:15]
	s_nop 0
	v_mfma_f32_32x32x16_bf16 v[80:95], v[56:59], v[28:31], v[80:95]
	v_mfma_f32_32x32x16_bf16 v[0:15], v[32:35], v[24:27], v[0:15]
	v_mfma_f32_32x32x16_bf16 v[80:95], v[40:43], v[24:27], v[80:95]
	v_mfma_f32_32x32x16_bf16 v[0:15], v[36:39], v[20:23], v[0:15]
	v_mfma_f32_32x32x16_bf16 v[80:95], v[44:47], v[20:23], v[80:95]
	v_mfma_f32_32x32x16_bf16 v[0:15], v[52:55], v[16:19], v[0:15]
	v_mfma_f32_32x32x16_bf16 v[80:95], v[60:63], v[16:19], v[80:95]
	v_lshl_add_u32 v48, s23, 9, v243
	s_and_b64 vcc, s[46:47], s[0:1]
	v_lshl_add_u32 v49, s22, 9, v243
	ds_read_b128 v[32:35], v48 offset:12320
	ds_read_b128 v[36:39], v48 offset:24640
	ds_read_b128 v[40:43], v49 offset:12320
	ds_read_b128 v[44:47], v49 offset:24640
	ds_read_b128 v[182:185], v48
	ds_read_b128 v[200:203], v48 offset:36960
	ds_read_b128 v[204:207], v49
	ds_read_b128 v[208:211], v49 offset:36960
	v_cndmask_b32_e32 v178, v186, v247, vcc
	v_add3_u32 v178, v178, v187, v250
	ds_read2_b32 v[64:65], v178 offset0:96 offset1:95
	ds_read2_b32 v[66:67], v178 offset0:94 offset1:93
	ds_read2_b32 v[68:69], v178 offset0:88 offset1:87
	ds_read2_b32 v[70:71], v178 offset0:86 offset1:85
	ds_read2_b32 v[72:73], v178 offset0:80 offset1:79
	ds_read2_b32 v[74:75], v178 offset0:78 offset1:77
	ds_read2_b32 v[76:77], v178 offset0:72 offset1:71
	ds_read2_b32 v[78:79], v178 offset0:70 offset1:69
	s_and_b64 vcc, s[46:47], s[42:43]
	v_cndmask_b32_e32 v179, v186, v248, vcc
	v_add3_u32 v179, v179, v187, v250
	s_waitcnt lgkmcnt(8)
	ds_read2_b32 v[48:49], v179 offset0:64 offset1:63
	ds_read2_b32 v[50:51], v179 offset0:62 offset1:61
	ds_read2_b32 v[52:53], v179 offset0:56 offset1:55
	ds_read2_b32 v[54:55], v179 offset0:54 offset1:53
	ds_read2_b32 v[56:57], v179 offset0:48 offset1:47
	ds_read2_b32 v[58:59], v179 offset0:46 offset1:45
	ds_read2_b32 v[60:61], v179 offset0:40 offset1:39
	ds_read2_b32 v[62:63], v179 offset0:38 offset1:37
	s_waitcnt lgkmcnt(0)
	v_mfma_f32_32x32x16_bf16 v[64:79], v[182:185], v[28:31], v[64:79]
	s_nop 0
	v_mfma_f32_32x32x16_bf16 v[48:63], v[204:207], v[28:31], v[48:63]
	v_mfma_f32_32x32x16_bf16 v[64:79], v[32:35], v[24:27], v[64:79]
	v_mfma_f32_32x32x16_bf16 v[48:63], v[40:43], v[24:27], v[48:63]
	v_mfma_f32_32x32x16_bf16 v[64:79], v[36:39], v[20:23], v[64:79]
	v_mfma_f32_32x32x16_bf16 v[48:63], v[44:47], v[20:23], v[48:63]
	v_mfma_f32_32x32x16_bf16 v[64:79], v[200:203], v[16:19], v[64:79]
	v_mfma_f32_32x32x16_bf16 v[48:63], v[208:211], v[16:19], v[48:63]
	v_lshl_add_u32 v32, s4, 9, v243
	s_and_b64 vcc, s[46:47], s[44:45]
	ds_read_b128 v[182:185], v32 offset:12320
	ds_read_b128 v[200:203], v32 offset:24640
	ds_read_b128 v[204:207], v32
	ds_read_b128 v[208:211], v32 offset:36960
	v_cndmask_b32_e32 v178, v186, v249, vcc
	v_add3_u32 v178, v178, v187, v250
	ds_read2_b32 v[32:33], v178 offset0:32 offset1:31
	ds_read2_b32 v[34:35], v178 offset0:30 offset1:29
	ds_read2_b32 v[36:37], v178 offset0:24 offset1:23
	ds_read2_b32 v[38:39], v178 offset0:22 offset1:21
	ds_read2_b32 v[40:41], v178 offset0:16 offset1:15
	ds_read2_b32 v[42:43], v178 offset0:14 offset1:13
	ds_read2_b32 v[44:45], v178 offset0:8 offset1:7
	ds_read2_b32 v[46:47], v178 offset0:6 offset1:5
	s_waitcnt lgkmcnt(0)
; #define LAS __attribute__((address_space(3)))
; __device__ __forceinline__ void attn_phase(LAS unsigned char* lds, const bf16_t* qp, const bf16_t* kvp, bf16_t* obuf, float* lse, const float* biasG, const int gi, const int rsh, const int G) {
;     ...
;                 p[c2] = __builtin_amdgcn_mfma_f32_32x32x16_bf16(ka[d0], qr[d0], p[c2], 0, 0, 0);
;                 if (c2 + 1 < 5) p[c2 + 1 < 5 ? c2 + 1 : c2] = __builtin_amdgcn_mfma_f32_32x32x16_bf16(kb[d0], qr[d0], p[c2 + 1 < 5 ? c2 + 1 : c2], 0, 0, 0);
;             }
;             __builtin_amdgcn_sched_barrier(0);
;         }
;         float mx = p[0][0];
; #pragma unroll
;         for (int cc = 0; cc < 5; ++cc)
; #pragma unroll
;             for (int r = 0; r < 16; ++r) mx = fmaxf(mx, p[cc][r]);
;         mx = fmaxf(mx, __shfl_xor(mx, 32));
;         typedef float f32x2 __attribute__((ext_vector_type(2)));
;         f32x2 l2 = (f32x2){0.f, 0.f};
;     ...
;         ATT_EXP8(0, 0); ATT_EXP8(0, 8);
;         bf16_t* og = obuf + ((size_t)h * M + growq) * 64 + 8 * hi;
;         u32x4 prev[2][2];
;         f32x16 o[2];
; #pragma unroll
;         for (int r = 0; r < 16; ++r) { o[0][r] = 0.f; o[1][r] = 0.f; }
;         const LAS unsigned char* vb = lds + A_V0 + ((lane >> 4) & 1) * 32 + (lane & 3) * 8 + (4 * hi + ((lane & 15) >> 2)) * 64;
; #pragma unroll
;         for (int cc = 0; cc < 5; ++cc)
; #pragma unroll
;             for (int gk = 0; gk < 2; ++gk) {
;                 if (cc == 3 && gk == 0 && gi > 0) {
; #pragma unroll
;                     for (int d0 = 0; d0 < 2; ++d0)
; #pragma unroll
;                         for (int pr = 0; pr < 2; ++pr) prev[d0][pr] = gld<u32x4>(og + 32 * d0 + 16 * pr);
;                 }
;                 if (cc + 1 < 5) ATT_EXP8(cc + 1 < 5 ? cc + 1 : cc, 8 * gk);
;                 u32x4 pw; pw.x = cvt_pk_bf16(p[cc][8 * gk + 0], p[cc][8 * gk + 1]); pw.y = cvt_pk_bf16(p[cc][8 * gk + 2], p[cc][8 * gk + 3]);
;                 pw.z = cvt_pk_bf16(p[cc][8 * gk + 4], p[cc][8 * gk + 5]); pw.w = cvt_pk_bf16(p[cc][8 * gk + 6], p[cc][8 * gk + 7]);
;                 const bf16x8 pa = __builtin_bit_cast(bf16x8, pw);
;                 const LAS unsigned char* vrow = vb + sc[cc] * 2048 + gk * 1024;
; #pragma unroll
;                 for (int d0 = 0; d0 < 2; ++d0) {
;                     const v4i16_t lo = vtr(vrow + d0 * VHS), hh = vtr(vrow + d0 * VHS + 512);
	s_nop 1
	v_mfma_f32_32x32x16_bf16 v[32:47], v[204:207], v[28:31], v[32:47]
	v_mfma_f32_32x32x16_bf16 v[32:47], v[182:185], v[24:27], v[32:47]
	v_mfma_f32_32x32x16_bf16 v[32:47], v[200:203], v[20:23], v[32:47]
	v_mfma_f32_32x32x16_bf16 v[32:47], v[208:211], v[16:19], v[32:47]
	v_max_f32_e32 v16, v1, v1
	v_max_f32_e32 v17, v0, v0
	v_max_f32_e32 v16, v17, v16
	v_max3_f32 v16, v16, v2, v3
	v_max3_f32 v16, v16, v4, v5
	v_max3_f32 v16, v16, v6, v7
	v_max3_f32 v16, v16, v8, v9
	v_max3_f32 v16, v16, v10, v11
	v_max3_f32 v16, v16, v12, v13
	v_max3_f32 v16, v16, v14, v15
	v_max3_f32 v16, v16, v80, v81
	v_max3_f32 v16, v16, v82, v83
	v_max3_f32 v16, v16, v84, v85
	v_max3_f32 v16, v16, v86, v87
	v_max3_f32 v16, v16, v88, v89
	v_max3_f32 v16, v16, v90, v91
	v_max3_f32 v16, v16, v92, v93
	v_max3_f32 v16, v16, v94, v95
	v_max3_f32 v16, v16, v64, v65
	v_max3_f32 v16, v16, v66, v67
	v_max3_f32 v16, v16, v68, v69
	v_max3_f32 v16, v16, v70, v71
	v_max3_f32 v16, v16, v72, v73
	v_max3_f32 v16, v16, v74, v75
	v_max3_f32 v16, v16, v76, v77
	v_max3_f32 v16, v16, v78, v79
	v_max3_f32 v16, v16, v48, v49
	v_max3_f32 v16, v16, v50, v51
	v_max3_f32 v16, v16, v52, v53
	v_max3_f32 v16, v16, v54, v55
	v_max3_f32 v16, v16, v56, v57
	v_max3_f32 v16, v16, v58, v59
	v_max3_f32 v16, v16, v60, v61
	v_max3_f32 v16, v16, v62, v63
	v_max3_f32 v16, v16, v32, v33
	v_max3_f32 v16, v16, v34, v35
	v_max3_f32 v16, v16, v36, v37
	v_max3_f32 v16, v16, v38, v39
	v_and_b32_e32 v18, 64, v233
	v_max3_f32 v16, v16, v40, v41
	v_xor_b32_e32 v17, 32, v233
	v_add_u32_e32 v18, 64, v18
	v_max3_f32 v16, v16, v42, v43
	v_cmp_lt_i32_e32 vcc, v17, v18
	v_max3_f32 v16, v16, v44, v45
	v_max3_f32 v16, v16, v46, v47
	v_cndmask_b32_e32 v17, v233, v17, vcc
	v_lshlrev_b32_e32 v228, 2, v17
	ds_bpermute_b32 v17, v228, v16
	s_lshl_b32 s2, s19, 22
	v_readlane_b32 s3, v255, 21
	s_add_u32 s2, s3, s2
	v_readlane_b32 s3, v255, 22
	s_waitcnt lgkmcnt(0)
	v_max_f32_e32 v17, v17, v17
	v_max_f32_e32 v200, v16, v17
	v_pk_add_f32 v[0:1], v[0:1], v[200:201] op_sel_hi:[1,0] neg_lo:[0,1] neg_hi:[0,1]
	s_addc_u32 s3, s3, 0
	v_exp_f32_e32 v202, v0
	v_exp_f32_e32 v203, v1
	v_pk_add_f32 v[0:1], v[2:3], v[200:201] op_sel_hi:[1,0] neg_lo:[0,1] neg_hi:[0,1]
	v_mov_b32_e32 v191, v96
	v_exp_f32_e32 v204, v0
	v_exp_f32_e32 v205, v1
	v_pk_add_f32 v[0:1], v[4:5], v[200:201] op_sel_hi:[1,0] neg_lo:[0,1] neg_hi:[0,1]
	v_lshl_add_u32 v178, s27, 11, v244
	v_exp_f32_e32 v206, v0
	v_exp_f32_e32 v207, v1
	v_pk_add_f32 v[0:1], v[6:7], v[200:201] op_sel_hi:[1,0] neg_lo:[0,1] neg_hi:[0,1]
	v_add_u32_e32 v179, 0xc080, v178
	v_exp_f32_e32 v208, v0
	v_exp_f32_e32 v209, v1
	v_pk_add_f32 v[0:1], v[8:9], v[200:201] op_sel_hi:[1,0] neg_lo:[0,1] neg_hi:[0,1]
	v_pk_add_f32 v[64:65], v[64:65], v[200:201] op_sel_hi:[1,0] neg_lo:[0,1] neg_hi:[0,1]
	v_exp_f32_e32 v210, v0
	v_exp_f32_e32 v211, v1
	v_pk_add_f32 v[0:1], v[10:11], v[200:201] op_sel_hi:[1,0] neg_lo:[0,1] neg_hi:[0,1]
	s_and_b64 vcc, exec, s[54:55]
	v_exp_f32_e32 v212, v0
	v_exp_f32_e32 v213, v1
	v_pk_add_f32 v[0:1], v[12:13], v[200:201] op_sel_hi:[1,0] neg_lo:[0,1] neg_hi:[0,1]
	s_nop 0
	v_exp_f32_e32 v214, v0
	v_exp_f32_e32 v215, v1
	v_pk_add_f32 v[0:1], v[14:15], v[200:201] op_sel_hi:[1,0] neg_lo:[0,1] neg_hi:[0,1]
	s_nop 0
	v_exp_f32_e32 v216, v0
	v_exp_f32_e32 v217, v1
	v_lshlrev_b64 v[0:1], 7, v[198:199]
	v_lshl_add_u64 v[0:1], s[2:3], 0, v[0:1]
	v_lshl_add_u64 v[198:199], v[0:1], 0, v[190:191]
	v_pk_add_f32 v[0:1], v[80:81], v[200:201] op_sel_hi:[1,0] neg_lo:[0,1] neg_hi:[0,1]
	s_nop 0
	v_exp_f32_e32 v80, v0
	v_exp_f32_e32 v81, v1
	v_pk_add_f32 v[0:1], v[82:83], v[200:201] op_sel_hi:[1,0] neg_lo:[0,1] neg_hi:[0,1]
	s_nop 0
	v_exp_f32_e32 v218, v0
	v_exp_f32_e32 v219, v1
	v_pk_add_f32 v[0:1], v[84:85], v[200:201] op_sel_hi:[1,0] neg_lo:[0,1] neg_hi:[0,1]
	s_nop 0
	v_exp_f32_e32 v84, v0
	v_exp_f32_e32 v85, v1
	v_pk_add_f32 v[0:1], v[86:87], v[200:201] op_sel_hi:[1,0] neg_lo:[0,1] neg_hi:[0,1]
	v_pk_add_f32 v[86:87], v[88:89], v[200:201] op_sel_hi:[1,0] neg_lo:[0,1] neg_hi:[0,1]
	v_exp_f32_e32 v82, v0
	v_exp_f32_e32 v83, v1
	v_cvt_pk_bf16_f32 v0, v202, v203
	v_cvt_pk_bf16_f32 v1, v204, v205
	v_cvt_pk_bf16_f32 v2, v206, v207
	v_cvt_pk_bf16_f32 v3, v208, v209
	ds_read_b64_tr_b16 v[4:5], v178 offset:49280
	ds_read_b64_tr_b16 v[6:7], v178 offset:49792
	s_waitcnt lgkmcnt(0)
; __device__ __forceinline__ unsigned cvt_pk_bf16(float lo, float hi) { unsigned r; asm volatile("v_cvt_pk_bf16_f32 %0, %1, %2" : "=v"(r) : "v"(lo), "v"(hi)); return r; }
; #define LAS __attribute__((address_space(3)))
; __device__ __forceinline__ v4i16_t vtr(const LAS unsigned char* p) { return __builtin_amdgcn_ds_read_tr16_b64_v4i16((LAS v4i16_t*)p); }
; #define ATT_EXP8(cc_, r0_) do { _Pragma("unroll") for (int r = (r0_); r < (r0_) + 8; r += 2) { \
;                 const f32x2 d_ = (f32x2){p[cc_][r], p[cc_][r + 1]} - mx; f32x2 e_; e_.x = __builtin_amdgcn_exp2f(d_.x); e_.y = __builtin_amdgcn_exp2f(d_.y); \
;                 p[cc_][r] = e_.x; p[cc_][r + 1] = e_.y; l2 += e_; } } while (0)
; __device__ __forceinline__ void attn_phase(LAS unsigned char* lds, const bf16_t* qp, const bf16_t* kvp, bf16_t* obuf, float* lse, const float* biasG, const int gi, const int rsh, const int G) {
;     ...
;         for (int cc = 0; cc < 5; ++cc)
; #pragma unroll
;             for (int gk = 0; gk < 2; ++gk) {
;                 if (cc == 3 && gk == 0 && gi > 0) {
; #pragma unroll
;                     for (int d0 = 0; d0 < 2; ++d0)
; #pragma unroll
;                         for (int pr = 0; pr < 2; ++pr) prev[d0][pr] = gld<u32x4>(og + 32 * d0 + 16 * pr);
;                 }
;                 if (cc + 1 < 5) ATT_EXP8(cc + 1 < 5 ? cc + 1 : cc, 8 * gk);
;                 u32x4 pw; pw.x = cvt_pk_bf16(p[cc][8 * gk + 0], p[cc][8 * gk + 1]); pw.y = cvt_pk_bf16(p[cc][8 * gk + 2], p[cc][8 * gk + 3]);
;                 pw.z = cvt_pk_bf16(p[cc][8 * gk + 4], p[cc][8 * gk + 5]); pw.w = cvt_pk_bf16(p[cc][8 * gk + 6], p[cc][8 * gk + 7]);
;                 const bf16x8 pa = __builtin_bit_cast(bf16x8, pw);
;                 const LAS unsigned char* vrow = vb + sc[cc] * 2048 + gk * 1024;
; #pragma unroll
;                 for (int d0 = 0; d0 < 2; ++d0) {
;                     const v4i16_t lo = vtr(vrow + d0 * VHS), hh = vtr(vrow + d0 * VHS + 512);
;                     const bf16x8 vf = (bf16x8){lo[0], lo[1], lo[2], lo[3], hh[0], hh[1], hh[2], hh[3]};
;                     o[d0] = __builtin_amdgcn_mfma_f32_32x32x16_bf16(vf, pa, o[d0], 0, 0, 0);
;                 }
;             }
	v_mfma_f32_32x32x16_bf16 v[16:31], v[4:7], v[0:3], 0
	ds_read_b64_tr_b16 v[4:5], v179 offset:24640
	ds_read_b64_tr_b16 v[6:7], v179 offset:25152
	v_exp_f32_e32 v220, v86
	v_exp_f32_e32 v221, v87
	v_pk_add_f32 v[86:87], v[90:91], v[200:201] op_sel_hi:[1,0] neg_lo:[0,1] neg_hi:[0,1]
	s_nop 0
	v_exp_f32_e32 v90, v86
	v_exp_f32_e32 v91, v87
	v_pk_add_f32 v[86:87], v[92:93], v[200:201] op_sel_hi:[1,0] neg_lo:[0,1] neg_hi:[0,1]
	v_cvt_pk_bf16_f32 v92, v210, v211
	v_cvt_pk_bf16_f32 v93, v212, v213
	s_waitcnt lgkmcnt(0)
	v_mfma_f32_32x32x16_bf16 v[0:15], v[4:7], v[0:3], 0
	ds_read_b64_tr_b16 v[182:183], v178 offset:50304
	ds_read_b64_tr_b16 v[184:185], v178 offset:50816
	v_exp_f32_e32 v88, v86
	v_exp_f32_e32 v89, v87
	v_pk_add_f32 v[86:87], v[94:95], v[200:201] op_sel_hi:[1,0] neg_lo:[0,1] neg_hi:[0,1]
	v_cvt_pk_bf16_f32 v94, v214, v215
	v_cvt_pk_bf16_f32 v95, v216, v217
	v_lshl_add_u32 v178, s26, 11, v244
	s_waitcnt lgkmcnt(0)
	v_mfma_f32_32x32x16_bf16 v[16:31], v[182:185], v[92:95], v[16:31]
	ds_read_b64_tr_b16 v[182:183], v179 offset:25664
	ds_read_b64_tr_b16 v[184:185], v179 offset:26176
	v_add_u32_e32 v179, 0xc080, v178
	v_exp_f32_e32 v86, v86
	v_exp_f32_e32 v87, v87
	s_waitcnt lgkmcnt(0)
	v_mfma_f32_32x32x16_bf16 v[0:15], v[182:185], v[92:95], v[0:15]
	ds_read_b64_tr_b16 v[182:183], v178 offset:49280
	ds_read_b64_tr_b16 v[184:185], v178 offset:49792
	v_exp_f32_e32 v94, v64
	v_exp_f32_e32 v95, v65
	v_pk_add_f32 v[64:65], v[66:67], v[200:201] op_sel_hi:[1,0] neg_lo:[0,1] neg_hi:[0,1]
	s_nop 0
	v_exp_f32_e32 v92, v64
	v_exp_f32_e32 v93, v65
	v_pk_add_f32 v[64:65], v[68:69], v[200:201] op_sel_hi:[1,0] neg_lo:[0,1] neg_hi:[0,1]
	v_cvt_pk_bf16_f32 v68, v80, v81
	v_cvt_pk_bf16_f32 v69, v218, v219
	s_nop 0
	v_exp_f32_e32 v66, v64
	v_exp_f32_e32 v67, v65
	v_pk_add_f32 v[64:65], v[70:71], v[200:201] op_sel_hi:[1,0] neg_lo:[0,1] neg_hi:[0,1]
	v_cvt_pk_bf16_f32 v70, v84, v85
	v_cvt_pk_bf16_f32 v71, v82, v83
	s_waitcnt lgkmcnt(0)
	v_mfma_f32_32x32x16_bf16 v[16:31], v[182:185], v[68:71], v[16:31]
	ds_read_b64_tr_b16 v[182:183], v179 offset:24640
	ds_read_b64_tr_b16 v[184:185], v179 offset:25152
	v_exp_f32_e32 v64, v64
	v_exp_f32_e32 v65, v65
	s_waitcnt lgkmcnt(0)
	v_mfma_f32_32x32x16_bf16 v[0:15], v[182:185], v[68:71], v[0:15]
	ds_read_b64_tr_b16 v[182:183], v178 offset:50304
	ds_read_b64_tr_b16 v[184:185], v178 offset:50816
	v_add_f32_e64 v68, v72, -v200
	v_add_f32_e64 v69, v73, -v200
	v_exp_f32_e32 v222, v68
	v_exp_f32_e32 v223, v69
	v_pk_add_f32 v[68:69], v[74:75], v[200:201] op_sel_hi:[1,0] neg_lo:[0,1] neg_hi:[0,1]
	v_cvt_pk_bf16_f32 v74, v220, v221
	v_cvt_pk_bf16_f32 v75, v90, v91
	s_nop 0
	v_exp_f32_e32 v72, v68
	v_exp_f32_e32 v73, v69
	v_pk_add_f32 v[68:69], v[76:77], v[200:201] op_sel_hi:[1,0] neg_lo:[0,1] neg_hi:[0,1]
	v_cvt_pk_bf16_f32 v76, v88, v89
	v_cvt_pk_bf16_f32 v77, v86, v87
	s_waitcnt lgkmcnt(0)
	v_mfma_f32_32x32x16_bf16 v[16:31], v[182:185], v[74:77], v[16:31]
	ds_read_b64_tr_b16 v[182:183], v179 offset:25664
	ds_read_b64_tr_b16 v[184:185], v179 offset:26176
	v_exp_f32_e32 v70, v68
	v_exp_f32_e32 v71, v69
	v_pk_add_f32 v[68:69], v[78:79], v[200:201] op_sel_hi:[1,0] neg_lo:[0,1] neg_hi:[0,1]
	v_lshl_add_u32 v78, s23, 11, v244
	v_add_u32_e32 v79, 0xc080, v78
	v_exp_f32_e32 v68, v68
	s_waitcnt lgkmcnt(0)
	v_mfma_f32_32x32x16_bf16 v[0:15], v[182:185], v[74:77], v[0:15]
	ds_read_b64_tr_b16 v[182:183], v78 offset:49280
	ds_read_b64_tr_b16 v[184:185], v78 offset:49792
	v_cvt_pk_bf16_f32 v74, v94, v95
	v_cvt_pk_bf16_f32 v75, v92, v93
	v_cvt_pk_bf16_f32 v76, v66, v67
	v_cvt_pk_bf16_f32 v77, v64, v65
	v_exp_f32_e32 v69, v69
	s_waitcnt lgkmcnt(0)
	v_mfma_f32_32x32x16_bf16 v[16:31], v[182:185], v[74:77], v[16:31]
	ds_read_b64_tr_b16 v[182:183], v79 offset:24640
	ds_read_b64_tr_b16 v[184:185], v79 offset:25152
	s_waitcnt lgkmcnt(0)
	v_mfma_f32_32x32x16_bf16 v[0:15], v[182:185], v[74:77], v[0:15]
	ds_read_b64_tr_b16 v[182:183], v78 offset:50304
	ds_read_b64_tr_b16 v[184:185], v78 offset:50816
	v_cvt_pk_bf16_f32 v74, v222, v223
	v_cvt_pk_bf16_f32 v75, v72, v73
	v_cvt_pk_bf16_f32 v76, v70, v71
	v_cvt_pk_bf16_f32 v77, v68, v69
	s_waitcnt lgkmcnt(0)
	v_mfma_f32_32x32x16_bf16 v[16:31], v[182:185], v[74:77], v[16:31]
	ds_read_b64_tr_b16 v[182:183], v79 offset:25664
	ds_read_b64_tr_b16 v[184:185], v79 offset:26176
	s_waitcnt lgkmcnt(0)
	v_mfma_f32_32x32x16_bf16 v[0:15], v[182:185], v[74:77], v[0:15]
	s_cbranch_vccnz .LBB0_117
	global_load_dwordx4 v[158:161], v[198:199], off
	global_load_dwordx4 v[154:157], v[198:199], off offset:32
	global_load_dwordx4 v[150:153], v[198:199], off offset:64
	global_load_dwordx4 v[146:149], v[198:199], off offset:96
